# both P11 table-build copies rewritten (the executed one was still the serialized loop)
# speedup vs baseline: 1.0053x; 1.0053x over previous
; #define LAS __attribute__((address_space(3)))
; __device__ __forceinline__ void build_tbl(const f32x2* PS, int pm, LAS unsigned char* lds, int wid, int lane) {
;     LAS f32x2* tbl = (LAS f32x2*)(lds + TBL_OFF);
;     const f32x2* p = PS + ((size_t)pm * BM + wid * 32) * 64 + lane;
; #pragma unroll 8
;     for (int i = 0; i < 32; ++i) {
;         const f32x2 v = p[(size_t)i * 64];
;         const float a = wave_sum(v.x), b = wave_sum(v.y);
;         if (lane == 0) { const float mu = a * (1.f / DM), var = fmaxf(b * (1.f / DM) - mu * mu, 0.f); tbl[wid * 32 + i] = (f32x2){mu, 1.f / sqrtf(var + LN_EPS)}; }
.LBB0_953:
	s_waitcnt lgkmcnt(0)
	v_readfirstlane_b32 s5, v182
	s_ashr_i32 s65, s64, 31
	s_cmp_eq_u32 s5, s4
	s_cbranch_scc1 .LBB0_975
	s_ashr_i32 s65, s64, 31
	s_lshl_b64 s[18:19], s[64:65], 17
	v_lshl_add_u64 v[230:231], v[162:163], 0, s[18:19]
	s_mov_b64 s[18:19], 0x1000
	global_load_dwordx2 v[128:129], v[230:231], off offset:-2048
	global_load_dwordx2 v[130:131], v[230:231], off offset:-1536
	global_load_dwordx2 v[132:133], v[230:231], off offset:-1024
	global_load_dwordx2 v[134:135], v[230:231], off offset:-512
	global_load_dwordx2 v[136:137], v[230:231], off
	global_load_dwordx2 v[138:139], v[230:231], off offset:512
	global_load_dwordx2 v[140:141], v[230:231], off offset:1024
	global_load_dwordx2 v[142:143], v[230:231], off offset:1536
	v_lshl_add_u64 v[230:231], v[230:231], 0, s[18:19]
	global_load_dwordx2 v[182:183], v[230:231], off offset:-2048
	global_load_dwordx2 v[184:185], v[230:231], off offset:-1536
	global_load_dwordx2 v[186:187], v[230:231], off offset:-1024
	global_load_dwordx2 v[188:189], v[230:231], off offset:-512
	global_load_dwordx2 v[190:191], v[230:231], off
	global_load_dwordx2 v[192:193], v[230:231], off offset:512
	global_load_dwordx2 v[194:195], v[230:231], off offset:1024
	global_load_dwordx2 v[196:197], v[230:231], off offset:1536
	v_lshl_add_u64 v[230:231], v[230:231], 0, s[18:19]
	global_load_dwordx2 v[198:199], v[230:231], off offset:-2048
	global_load_dwordx2 v[200:201], v[230:231], off offset:-1536
	global_load_dwordx2 v[202:203], v[230:231], off offset:-1024
	global_load_dwordx2 v[204:205], v[230:231], off offset:-512
	global_load_dwordx2 v[206:207], v[230:231], off
	global_load_dwordx2 v[208:209], v[230:231], off offset:512
	global_load_dwordx2 v[210:211], v[230:231], off offset:1024
	global_load_dwordx2 v[212:213], v[230:231], off offset:1536
	v_lshl_add_u64 v[230:231], v[230:231], 0, s[18:19]
	global_load_dwordx2 v[214:215], v[230:231], off offset:-2048
	global_load_dwordx2 v[216:217], v[230:231], off offset:-1536
	global_load_dwordx2 v[218:219], v[230:231], off offset:-1024
	global_load_dwordx2 v[220:221], v[230:231], off offset:-512
	global_load_dwordx2 v[222:223], v[230:231], off
	global_load_dwordx2 v[224:225], v[230:231], off offset:512
	global_load_dwordx2 v[226:227], v[230:231], off offset:1024
	global_load_dwordx2 v[228:229], v[230:231], off offset:1536
	s_waitcnt vmcnt(0)
	v_permlane32_swap_b32_e32 v128, v198
	v_permlane32_swap_b32_e32 v129, v199
	v_permlane32_swap_b32_e32 v130, v200
	v_permlane32_swap_b32_e32 v131, v201
	v_permlane32_swap_b32_e32 v132, v202
	v_permlane32_swap_b32_e32 v133, v203
	v_permlane32_swap_b32_e32 v134, v204
	v_permlane32_swap_b32_e32 v135, v205
	v_permlane32_swap_b32_e32 v136, v206
	v_permlane32_swap_b32_e32 v137, v207
	v_permlane32_swap_b32_e32 v138, v208
	v_permlane32_swap_b32_e32 v139, v209
	v_permlane32_swap_b32_e32 v140, v210
	v_permlane32_swap_b32_e32 v141, v211
	v_permlane32_swap_b32_e32 v142, v212
	v_permlane32_swap_b32_e32 v143, v213
	v_permlane32_swap_b32_e32 v182, v214
	v_permlane32_swap_b32_e32 v183, v215
	v_permlane32_swap_b32_e32 v184, v216
	v_permlane32_swap_b32_e32 v185, v217
	v_permlane32_swap_b32_e32 v186, v218
	v_permlane32_swap_b32_e32 v187, v219
	v_permlane32_swap_b32_e32 v188, v220
	v_permlane32_swap_b32_e32 v189, v221
	v_permlane32_swap_b32_e32 v190, v222
	v_permlane32_swap_b32_e32 v191, v223
	v_permlane32_swap_b32_e32 v192, v224
	v_permlane32_swap_b32_e32 v193, v225
	v_permlane32_swap_b32_e32 v194, v226
	v_permlane32_swap_b32_e32 v195, v227
	v_permlane32_swap_b32_e32 v196, v228
	v_permlane32_swap_b32_e32 v197, v229
	v_pk_add_f32 v[128:129], v[128:129], v[198:199]
	v_pk_add_f32 v[130:131], v[130:131], v[200:201]
	v_pk_add_f32 v[132:133], v[132:133], v[202:203]
	v_pk_add_f32 v[134:135], v[134:135], v[204:205]
	v_pk_add_f32 v[136:137], v[136:137], v[206:207]
	v_pk_add_f32 v[138:139], v[138:139], v[208:209]
	v_pk_add_f32 v[140:141], v[140:141], v[210:211]
	v_pk_add_f32 v[142:143], v[142:143], v[212:213]
	v_pk_add_f32 v[182:183], v[182:183], v[214:215]
	v_pk_add_f32 v[184:185], v[184:185], v[216:217]
	v_pk_add_f32 v[186:187], v[186:187], v[218:219]
	v_pk_add_f32 v[188:189], v[188:189], v[220:221]
	v_pk_add_f32 v[190:191], v[190:191], v[222:223]
	v_pk_add_f32 v[192:193], v[192:193], v[224:225]
	v_pk_add_f32 v[194:195], v[194:195], v[226:227]
	v_pk_add_f32 v[196:197], v[196:197], v[228:229]
	s_nop 1
	v_permlane16_swap_b32_e32 v128, v182
	v_permlane16_swap_b32_e32 v129, v183
	v_permlane16_swap_b32_e32 v130, v184
	v_permlane16_swap_b32_e32 v131, v185
	v_permlane16_swap_b32_e32 v132, v186
	v_permlane16_swap_b32_e32 v133, v187
	v_permlane16_swap_b32_e32 v134, v188
	v_permlane16_swap_b32_e32 v135, v189
	v_permlane16_swap_b32_e32 v136, v190
	v_permlane16_swap_b32_e32 v137, v191
	v_permlane16_swap_b32_e32 v138, v192
	v_permlane16_swap_b32_e32 v139, v193
	v_permlane16_swap_b32_e32 v140, v194
	v_permlane16_swap_b32_e32 v141, v195
	v_permlane16_swap_b32_e32 v142, v196
	v_permlane16_swap_b32_e32 v143, v197
	v_pk_add_f32 v[128:129], v[128:129], v[182:183]
	v_pk_add_f32 v[130:131], v[130:131], v[184:185]
	v_pk_add_f32 v[132:133], v[132:133], v[186:187]
	v_pk_add_f32 v[134:135], v[134:135], v[188:189]
	v_pk_add_f32 v[136:137], v[136:137], v[190:191]
	v_pk_add_f32 v[138:139], v[138:139], v[192:193]
	v_pk_add_f32 v[140:141], v[140:141], v[194:195]
	v_pk_add_f32 v[142:143], v[142:143], v[196:197]
	s_nop 1
	v_add_f32_dpp v128, v128, v128 row_ror:8 row_mask:0xf bank_mask:0xf
	v_add_f32_dpp v129, v129, v129 row_ror:8 row_mask:0xf bank_mask:0xf
	v_add_f32_dpp v130, v130, v130 row_ror:8 row_mask:0xf bank_mask:0xf
	v_add_f32_dpp v131, v131, v131 row_ror:8 row_mask:0xf bank_mask:0xf
; __device__ __forceinline__ void build_tbl(const f32x2* PS, int pm, LAS unsigned char* lds, int wid, int lane) {
;     ...
;         const float a = wave_sum(v.x), b = wave_sum(v.y);
;         if (lane == 0) { const float mu = a * (1.f / DM), var = fmaxf(b * (1.f / DM) - mu * mu, 0.f); tbl[wid * 32 + i] = (f32x2){mu, 1.f / sqrtf(var + LN_EPS)}; }
	v_add_f32_dpp v132, v132, v132 row_ror:8 row_mask:0xf bank_mask:0xf
	v_add_f32_dpp v133, v133, v133 row_ror:8 row_mask:0xf bank_mask:0xf
	v_add_f32_dpp v134, v134, v134 row_ror:8 row_mask:0xf bank_mask:0xf
	v_add_f32_dpp v135, v135, v135 row_ror:8 row_mask:0xf bank_mask:0xf
	v_add_f32_dpp v136, v136, v136 row_ror:8 row_mask:0xf bank_mask:0xf
	v_add_f32_dpp v137, v137, v137 row_ror:8 row_mask:0xf bank_mask:0xf
	v_add_f32_dpp v138, v138, v138 row_ror:8 row_mask:0xf bank_mask:0xf
	v_add_f32_dpp v139, v139, v139 row_ror:8 row_mask:0xf bank_mask:0xf
	v_add_f32_dpp v140, v140, v140 row_ror:8 row_mask:0xf bank_mask:0xf
	v_add_f32_dpp v141, v141, v141 row_ror:8 row_mask:0xf bank_mask:0xf
	v_add_f32_dpp v142, v142, v142 row_ror:8 row_mask:0xf bank_mask:0xf
	v_add_f32_dpp v143, v143, v143 row_ror:8 row_mask:0xf bank_mask:0xf
	v_add_f32_dpp v128, v128, v128 row_ror:4 row_mask:0xf bank_mask:0xf
	v_add_f32_dpp v129, v129, v129 row_ror:4 row_mask:0xf bank_mask:0xf
	v_add_f32_dpp v130, v130, v130 row_ror:4 row_mask:0xf bank_mask:0xf
	v_add_f32_dpp v131, v131, v131 row_ror:4 row_mask:0xf bank_mask:0xf
	v_add_f32_dpp v132, v132, v132 row_ror:4 row_mask:0xf bank_mask:0xf
	v_add_f32_dpp v133, v133, v133 row_ror:4 row_mask:0xf bank_mask:0xf
	v_add_f32_dpp v134, v134, v134 row_ror:4 row_mask:0xf bank_mask:0xf
	v_add_f32_dpp v135, v135, v135 row_ror:4 row_mask:0xf bank_mask:0xf
	v_add_f32_dpp v136, v136, v136 row_ror:4 row_mask:0xf bank_mask:0xf
	v_add_f32_dpp v137, v137, v137 row_ror:4 row_mask:0xf bank_mask:0xf
	v_add_f32_dpp v138, v138, v138 row_ror:4 row_mask:0xf bank_mask:0xf
	v_add_f32_dpp v139, v139, v139 row_ror:4 row_mask:0xf bank_mask:0xf
	v_add_f32_dpp v140, v140, v140 row_ror:4 row_mask:0xf bank_mask:0xf
	v_add_f32_dpp v141, v141, v141 row_ror:4 row_mask:0xf bank_mask:0xf
	v_add_f32_dpp v142, v142, v142 row_ror:4 row_mask:0xf bank_mask:0xf
	v_add_f32_dpp v143, v143, v143 row_ror:4 row_mask:0xf bank_mask:0xf
	v_add_f32_dpp v128, v128, v128 row_ror:2 row_mask:0xf bank_mask:0xf
	v_add_f32_dpp v129, v129, v129 row_ror:2 row_mask:0xf bank_mask:0xf
	v_add_f32_dpp v130, v130, v130 row_ror:2 row_mask:0xf bank_mask:0xf
	v_add_f32_dpp v131, v131, v131 row_ror:2 row_mask:0xf bank_mask:0xf
	v_add_f32_dpp v132, v132, v132 row_ror:2 row_mask:0xf bank_mask:0xf
	v_add_f32_dpp v133, v133, v133 row_ror:2 row_mask:0xf bank_mask:0xf
	v_add_f32_dpp v134, v134, v134 row_ror:2 row_mask:0xf bank_mask:0xf
	v_add_f32_dpp v135, v135, v135 row_ror:2 row_mask:0xf bank_mask:0xf
	v_add_f32_dpp v136, v136, v136 row_ror:2 row_mask:0xf bank_mask:0xf
	v_add_f32_dpp v137, v137, v137 row_ror:2 row_mask:0xf bank_mask:0xf
	v_add_f32_dpp v138, v138, v138 row_ror:2 row_mask:0xf bank_mask:0xf
	v_add_f32_dpp v139, v139, v139 row_ror:2 row_mask:0xf bank_mask:0xf
	v_add_f32_dpp v140, v140, v140 row_ror:2 row_mask:0xf bank_mask:0xf
	v_add_f32_dpp v141, v141, v141 row_ror:2 row_mask:0xf bank_mask:0xf
	v_add_f32_dpp v142, v142, v142 row_ror:2 row_mask:0xf bank_mask:0xf
	v_add_f32_dpp v143, v143, v143 row_ror:2 row_mask:0xf bank_mask:0xf
	v_add_f32_dpp v128, v128, v128 row_ror:1 row_mask:0xf bank_mask:0xf
	v_add_f32_dpp v129, v129, v129 row_ror:1 row_mask:0xf bank_mask:0xf
	v_add_f32_dpp v130, v130, v130 row_ror:1 row_mask:0xf bank_mask:0xf
	v_add_f32_dpp v131, v131, v131 row_ror:1 row_mask:0xf bank_mask:0xf
	v_add_f32_dpp v132, v132, v132 row_ror:1 row_mask:0xf bank_mask:0xf
	v_add_f32_dpp v133, v133, v133 row_ror:1 row_mask:0xf bank_mask:0xf
	v_add_f32_dpp v134, v134, v134 row_ror:1 row_mask:0xf bank_mask:0xf
	v_add_f32_dpp v135, v135, v135 row_ror:1 row_mask:0xf bank_mask:0xf
	v_add_f32_dpp v136, v136, v136 row_ror:1 row_mask:0xf bank_mask:0xf
	v_add_f32_dpp v137, v137, v137 row_ror:1 row_mask:0xf bank_mask:0xf
	v_add_f32_dpp v138, v138, v138 row_ror:1 row_mask:0xf bank_mask:0xf
	v_add_f32_dpp v139, v139, v139 row_ror:1 row_mask:0xf bank_mask:0xf
	v_add_f32_dpp v140, v140, v140 row_ror:1 row_mask:0xf bank_mask:0xf
	v_add_f32_dpp v141, v141, v141 row_ror:1 row_mask:0xf bank_mask:0xf
	v_add_f32_dpp v142, v142, v142 row_ror:1 row_mask:0xf bank_mask:0xf
	v_add_f32_dpp v143, v143, v143 row_ror:1 row_mask:0xf bank_mask:0xf
	s_nop 1
	v_mul_f32_e32 v128, s26, v128
	v_mul_f32_e32 v129, s26, v129
	v_fma_f32 v129, -v128, v128, v129
	v_max_f32_e32 v129, 0, v129
	v_add_f32_e32 v129, 0x3727c5ac, v129
	v_mul_f32_e32 v232, 0x4f800000, v129
	v_cmp_gt_f32_e32 vcc, s93, v129
	s_nop 1
	v_cndmask_b32_e32 v129, v129, v232, vcc
	v_sqrt_f32_e32 v232, v129
	s_nop 0
	v_add_u32_e32 v233, -1, v232
	v_fma_f32 v235, -v233, v232, v129
	v_add_u32_e32 v234, 1, v232
	v_cmp_ge_f32_e64 s[18:19], 0, v235
	s_nop 1
	v_cndmask_b32_e64 v233, v232, v233, s[18:19]
	v_fma_f32 v232, -v234, v232, v129
	v_cmp_lt_f32_e64 s[18:19], 0, v232
	s_nop 1
	v_cndmask_b32_e64 v232, v233, v234, s[18:19]
	v_mul_f32_e32 v233, 0x37800000, v232
	v_cndmask_b32_e32 v232, v232, v233, vcc
	v_cmp_class_f32_e32 vcc, v129, v178
	s_nop 1
	v_cndmask_b32_e32 v129, v232, v129, vcc
	v_div_scale_f32 v232, s[18:19], v129, v129, 1.0
	v_rcp_f32_e32 v233, v232
	s_nop 0
	v_fma_f32 v234, -v232, v233, 1.0
	v_fmac_f32_e32 v233, v234, v233
	v_div_scale_f32 v234, vcc, 1.0, v129, 1.0
	v_mul_f32_e32 v235, v234, v233
	v_fma_f32 v236, -v232, v235, v234
	v_fmac_f32_e32 v235, v236, v233
	v_fma_f32 v232, -v232, v235, v234
	v_div_fmas_f32 v232, v232, v233, v235
	v_div_fixup_f32 v129, v232, v129, 1.0
	v_mul_f32_e32 v130, s26, v130
	v_mul_f32_e32 v131, s26, v131
	v_fma_f32 v131, -v130, v130, v131
	v_max_f32_e32 v131, 0, v131
	v_add_f32_e32 v131, 0x3727c5ac, v131
	v_mul_f32_e32 v232, 0x4f800000, v131
	v_cmp_gt_f32_e32 vcc, s93, v131
	s_nop 1
	v_cndmask_b32_e32 v131, v131, v232, vcc
; __device__ __forceinline__ void build_tbl(const f32x2* PS, int pm, LAS unsigned char* lds, int wid, int lane) {
;     ...
;         if (lane == 0) { const float mu = a * (1.f / DM), var = fmaxf(b * (1.f / DM) - mu * mu, 0.f); tbl[wid * 32 + i] = (f32x2){mu, 1.f / sqrtf(var + LN_EPS)}; }
	v_sqrt_f32_e32 v232, v131
	s_nop 0
	v_add_u32_e32 v233, -1, v232
	v_fma_f32 v235, -v233, v232, v131
	v_add_u32_e32 v234, 1, v232
	v_cmp_ge_f32_e64 s[18:19], 0, v235
	s_nop 1
	v_cndmask_b32_e64 v233, v232, v233, s[18:19]
	v_fma_f32 v232, -v234, v232, v131
	v_cmp_lt_f32_e64 s[18:19], 0, v232
	s_nop 1
	v_cndmask_b32_e64 v232, v233, v234, s[18:19]
	v_mul_f32_e32 v233, 0x37800000, v232
	v_cndmask_b32_e32 v232, v232, v233, vcc
	v_cmp_class_f32_e32 vcc, v131, v178
	s_nop 1
	v_cndmask_b32_e32 v131, v232, v131, vcc
	v_div_scale_f32 v232, s[18:19], v131, v131, 1.0
	v_rcp_f32_e32 v233, v232
	s_nop 0
	v_fma_f32 v234, -v232, v233, 1.0
	v_fmac_f32_e32 v233, v234, v233
	v_div_scale_f32 v234, vcc, 1.0, v131, 1.0
	v_mul_f32_e32 v235, v234, v233
	v_fma_f32 v236, -v232, v235, v234
	v_fmac_f32_e32 v235, v236, v233
	v_fma_f32 v232, -v232, v235, v234
	v_div_fmas_f32 v232, v232, v233, v235
	v_div_fixup_f32 v131, v232, v131, 1.0
	v_mul_f32_e32 v132, s26, v132
	v_mul_f32_e32 v133, s26, v133
	v_fma_f32 v133, -v132, v132, v133
	v_max_f32_e32 v133, 0, v133
	v_add_f32_e32 v133, 0x3727c5ac, v133
	v_mul_f32_e32 v232, 0x4f800000, v133
	v_cmp_gt_f32_e32 vcc, s93, v133
	s_nop 1
	v_cndmask_b32_e32 v133, v133, v232, vcc
	v_sqrt_f32_e32 v232, v133
	s_nop 0
	v_add_u32_e32 v233, -1, v232
	v_fma_f32 v235, -v233, v232, v133
	v_add_u32_e32 v234, 1, v232
	v_cmp_ge_f32_e64 s[18:19], 0, v235
	s_nop 1
	v_cndmask_b32_e64 v233, v232, v233, s[18:19]
	v_fma_f32 v232, -v234, v232, v133
	v_cmp_lt_f32_e64 s[18:19], 0, v232
	s_nop 1
	v_cndmask_b32_e64 v232, v233, v234, s[18:19]
	v_mul_f32_e32 v233, 0x37800000, v232
	v_cndmask_b32_e32 v232, v232, v233, vcc
	v_cmp_class_f32_e32 vcc, v133, v178
	s_nop 1
	v_cndmask_b32_e32 v133, v232, v133, vcc
	v_div_scale_f32 v232, s[18:19], v133, v133, 1.0
	v_rcp_f32_e32 v233, v232
	s_nop 0
	v_fma_f32 v234, -v232, v233, 1.0
	v_fmac_f32_e32 v233, v234, v233
	v_div_scale_f32 v234, vcc, 1.0, v133, 1.0
	v_mul_f32_e32 v235, v234, v233
	v_fma_f32 v236, -v232, v235, v234
	v_fmac_f32_e32 v235, v236, v233
	v_fma_f32 v232, -v232, v235, v234
	v_div_fmas_f32 v232, v232, v233, v235
	v_div_fixup_f32 v133, v232, v133, 1.0
	v_mul_f32_e32 v134, s26, v134
	v_mul_f32_e32 v135, s26, v135
	v_fma_f32 v135, -v134, v134, v135
	v_max_f32_e32 v135, 0, v135
	v_add_f32_e32 v135, 0x3727c5ac, v135
	v_mul_f32_e32 v232, 0x4f800000, v135
	v_cmp_gt_f32_e32 vcc, s93, v135
	s_nop 1
	v_cndmask_b32_e32 v135, v135, v232, vcc
	v_sqrt_f32_e32 v232, v135
	s_nop 0
	v_add_u32_e32 v233, -1, v232
	v_fma_f32 v235, -v233, v232, v135
	v_add_u32_e32 v234, 1, v232
	v_cmp_ge_f32_e64 s[18:19], 0, v235
	s_nop 1
	v_cndmask_b32_e64 v233, v232, v233, s[18:19]
	v_fma_f32 v232, -v234, v232, v135
	v_cmp_lt_f32_e64 s[18:19], 0, v232
	s_nop 1
	v_cndmask_b32_e64 v232, v233, v234, s[18:19]
	v_mul_f32_e32 v233, 0x37800000, v232
	v_cndmask_b32_e32 v232, v232, v233, vcc
	v_cmp_class_f32_e32 vcc, v135, v178
	s_nop 1
	v_cndmask_b32_e32 v135, v232, v135, vcc
	v_div_scale_f32 v232, s[18:19], v135, v135, 1.0
	v_rcp_f32_e32 v233, v232
	s_nop 0
	v_fma_f32 v234, -v232, v233, 1.0
	v_fmac_f32_e32 v233, v234, v233
	v_div_scale_f32 v234, vcc, 1.0, v135, 1.0
	v_mul_f32_e32 v235, v234, v233
	v_fma_f32 v236, -v232, v235, v234
	v_fmac_f32_e32 v235, v236, v233
	v_fma_f32 v232, -v232, v235, v234
	v_div_fmas_f32 v232, v232, v233, v235
	v_div_fixup_f32 v135, v232, v135, 1.0
	v_mul_f32_e32 v136, s26, v136
	v_mul_f32_e32 v137, s26, v137
	v_fma_f32 v137, -v136, v136, v137
	v_max_f32_e32 v137, 0, v137
	v_add_f32_e32 v137, 0x3727c5ac, v137
	v_mul_f32_e32 v232, 0x4f800000, v137
	v_cmp_gt_f32_e32 vcc, s93, v137
	s_nop 1
	v_cndmask_b32_e32 v137, v137, v232, vcc
	v_sqrt_f32_e32 v232, v137
	s_nop 0
	v_add_u32_e32 v233, -1, v232
	v_fma_f32 v235, -v233, v232, v137
	v_add_u32_e32 v234, 1, v232
	v_cmp_ge_f32_e64 s[18:19], 0, v235
	s_nop 1
	v_cndmask_b32_e64 v233, v232, v233, s[18:19]
	v_fma_f32 v232, -v234, v232, v137
	v_cmp_lt_f32_e64 s[18:19], 0, v232
	s_nop 1
	v_cndmask_b32_e64 v232, v233, v234, s[18:19]
	v_mul_f32_e32 v233, 0x37800000, v232
	v_cndmask_b32_e32 v232, v232, v233, vcc
	v_cmp_class_f32_e32 vcc, v137, v178
	s_nop 1
	v_cndmask_b32_e32 v137, v232, v137, vcc
	v_div_scale_f32 v232, s[18:19], v137, v137, 1.0
	v_rcp_f32_e32 v233, v232
	s_nop 0
	v_fma_f32 v234, -v232, v233, 1.0
	v_fmac_f32_e32 v233, v234, v233
	v_div_scale_f32 v234, vcc, 1.0, v137, 1.0
	v_mul_f32_e32 v235, v234, v233
; #define LAS __attribute__((address_space(3)))
; __device__ __forceinline__ void build_tbl(const f32x2* PS, int pm, LAS unsigned char* lds, int wid, int lane) {
;     ...
;         if (lane == 0) { const float mu = a * (1.f / DM), var = fmaxf(b * (1.f / DM) - mu * mu, 0.f); tbl[wid * 32 + i] = (f32x2){mu, 1.f / sqrtf(var + LN_EPS)}; }
;     }
; }
; __device__ __forceinline__ void ensure_tbl(const f32x2* PS, int sid, int pm, const EpiCtx& X) {
;     volatile LAS unsigned* keyw = (volatile LAS unsigned*)(X.lds + MISC_OFF) + KEY_WORD;
;     const unsigned key = (unsigned)(sid * 64 + pm + 1);
;     if ((unsigned)__builtin_amdgcn_readfirstlane((int)keyw[0]) != key) {
;         build_tbl(PS, pm, X.lds, X.wid, X.lane);
;         asm volatile("s_waitcnt lgkmcnt(0)" ::: "memory"); __builtin_amdgcn_s_barrier(); asm volatile("" ::: "memory");
;         if (X.tid == 0) keyw[0] = key;
	v_fma_f32 v236, -v232, v235, v234
	v_fmac_f32_e32 v235, v236, v233
	v_fma_f32 v232, -v232, v235, v234
	v_div_fmas_f32 v232, v232, v233, v235
	v_div_fixup_f32 v137, v232, v137, 1.0
	v_mul_f32_e32 v138, s26, v138
	v_mul_f32_e32 v139, s26, v139
	v_fma_f32 v139, -v138, v138, v139
	v_max_f32_e32 v139, 0, v139
	v_add_f32_e32 v139, 0x3727c5ac, v139
	v_mul_f32_e32 v232, 0x4f800000, v139
	v_cmp_gt_f32_e32 vcc, s93, v139
	s_nop 1
	v_cndmask_b32_e32 v139, v139, v232, vcc
	v_sqrt_f32_e32 v232, v139
	s_nop 0
	v_add_u32_e32 v233, -1, v232
	v_fma_f32 v235, -v233, v232, v139
	v_add_u32_e32 v234, 1, v232
	v_cmp_ge_f32_e64 s[18:19], 0, v235
	s_nop 1
	v_cndmask_b32_e64 v233, v232, v233, s[18:19]
	v_fma_f32 v232, -v234, v232, v139
	v_cmp_lt_f32_e64 s[18:19], 0, v232
	s_nop 1
	v_cndmask_b32_e64 v232, v233, v234, s[18:19]
	v_mul_f32_e32 v233, 0x37800000, v232
	v_cndmask_b32_e32 v232, v232, v233, vcc
	v_cmp_class_f32_e32 vcc, v139, v178
	s_nop 1
	v_cndmask_b32_e32 v139, v232, v139, vcc
	v_div_scale_f32 v232, s[18:19], v139, v139, 1.0
	v_rcp_f32_e32 v233, v232
	s_nop 0
	v_fma_f32 v234, -v232, v233, 1.0
	v_fmac_f32_e32 v233, v234, v233
	v_div_scale_f32 v234, vcc, 1.0, v139, 1.0
	v_mul_f32_e32 v235, v234, v233
	v_fma_f32 v236, -v232, v235, v234
	v_fmac_f32_e32 v235, v236, v233
	v_fma_f32 v232, -v232, v235, v234
	v_div_fmas_f32 v232, v232, v233, v235
	v_div_fixup_f32 v139, v232, v139, 1.0
	v_mul_f32_e32 v140, s26, v140
	v_mul_f32_e32 v141, s26, v141
	v_fma_f32 v141, -v140, v140, v141
	v_max_f32_e32 v141, 0, v141
	v_add_f32_e32 v141, 0x3727c5ac, v141
	v_mul_f32_e32 v232, 0x4f800000, v141
	v_cmp_gt_f32_e32 vcc, s93, v141
	s_nop 1
	v_cndmask_b32_e32 v141, v141, v232, vcc
	v_sqrt_f32_e32 v232, v141
	s_nop 0
	v_add_u32_e32 v233, -1, v232
	v_fma_f32 v235, -v233, v232, v141
	v_add_u32_e32 v234, 1, v232
	v_cmp_ge_f32_e64 s[18:19], 0, v235
	s_nop 1
	v_cndmask_b32_e64 v233, v232, v233, s[18:19]
	v_fma_f32 v232, -v234, v232, v141
	v_cmp_lt_f32_e64 s[18:19], 0, v232
	s_nop 1
	v_cndmask_b32_e64 v232, v233, v234, s[18:19]
	v_mul_f32_e32 v233, 0x37800000, v232
	v_cndmask_b32_e32 v232, v232, v233, vcc
	v_cmp_class_f32_e32 vcc, v141, v178
	s_nop 1
	v_cndmask_b32_e32 v141, v232, v141, vcc
	v_div_scale_f32 v232, s[18:19], v141, v141, 1.0
	v_rcp_f32_e32 v233, v232
	s_nop 0
	v_fma_f32 v234, -v232, v233, 1.0
	v_fmac_f32_e32 v233, v234, v233
	v_div_scale_f32 v234, vcc, 1.0, v141, 1.0
	v_mul_f32_e32 v235, v234, v233
	v_fma_f32 v236, -v232, v235, v234
	v_fmac_f32_e32 v235, v236, v233
	v_fma_f32 v232, -v232, v235, v234
	v_div_fmas_f32 v232, v232, v233, v235
	v_div_fixup_f32 v141, v232, v141, 1.0
	v_mul_f32_e32 v142, s26, v142
	v_mul_f32_e32 v143, s26, v143
	v_fma_f32 v143, -v142, v142, v143
	v_max_f32_e32 v143, 0, v143
	v_add_f32_e32 v143, 0x3727c5ac, v143
	v_mul_f32_e32 v232, 0x4f800000, v143
	v_cmp_gt_f32_e32 vcc, s93, v143
	s_nop 1
	v_cndmask_b32_e32 v143, v143, v232, vcc
	v_sqrt_f32_e32 v232, v143
	s_nop 0
	v_add_u32_e32 v233, -1, v232
	v_fma_f32 v235, -v233, v232, v143
	v_add_u32_e32 v234, 1, v232
	v_cmp_ge_f32_e64 s[18:19], 0, v235
	s_nop 1
	v_cndmask_b32_e64 v233, v232, v233, s[18:19]
	v_fma_f32 v232, -v234, v232, v143
	v_cmp_lt_f32_e64 s[18:19], 0, v232
	s_nop 1
	v_cndmask_b32_e64 v232, v233, v234, s[18:19]
	v_mul_f32_e32 v233, 0x37800000, v232
	v_cndmask_b32_e32 v232, v232, v233, vcc
	v_cmp_class_f32_e32 vcc, v143, v178
	s_nop 1
	v_cndmask_b32_e32 v143, v232, v143, vcc
	v_div_scale_f32 v232, s[18:19], v143, v143, 1.0
	v_rcp_f32_e32 v233, v232
	s_nop 0
	v_fma_f32 v234, -v232, v233, 1.0
	v_fmac_f32_e32 v233, v234, v233
	v_div_scale_f32 v234, vcc, 1.0, v143, 1.0
	v_mul_f32_e32 v235, v234, v233
	v_fma_f32 v236, -v232, v235, v234
	v_fmac_f32_e32 v235, v236, v233
	v_fma_f32 v232, -v232, v235, v234
	v_div_fmas_f32 v232, v232, v233, v235
	v_div_fixup_f32 v143, v232, v143, 1.0
	v_lshrrev_b32_e32 v237, 4, v179
	v_lshlrev_b32_e32 v237, 6, v237
	s_add_i32 s18, s87, 0x20400
	v_add_u32_e32 v237, s18, v237
	s_mov_b64 s[68:69], exec
	s_mov_b32 exec_lo, 0x10001
	s_mov_b32 exec_hi, 0x10001
	ds_write_b64 v237, v[128:129]
	ds_write_b64 v237, v[130:131] offset:8
	ds_write_b64 v237, v[132:133] offset:16
	ds_write_b64 v237, v[134:135] offset:24
	ds_write_b64 v237, v[136:137] offset:32
	ds_write_b64 v237, v[138:139] offset:40
	ds_write_b64 v237, v[140:141] offset:48
	ds_write_b64 v237, v[142:143] offset:56
	s_mov_b64 exec, s[68:69]
